# attention QK^T: K fragment LDS reads pipelined 4 deep using spare registers v238-v249 (was one read + full wait per MFMA)
# speedup vs baseline: 1.0080x; 1.0026x over previous
.LBB0_560:
	ds_read_b128 v[66:69], v180 offset:49152
	ds_read_b128 v[208:211], v182 offset:49152
	ds_read_b128 v[238:241], v180 offset:57344
	ds_read_b128 v[242:245], v182 offset:57344
	ds_read_b128 v[246:249], v183 offset:49152
	s_cmp_lt_u32 s75, s63
	s_cselect_b64 s[38:39], -1, 0
	s_or_b64 s[38:39], s[30:31], s[38:39]
	s_and_b64 vcc, exec, s[38:39]
	v_add_u32_e32 v197, s71, v167
	s_waitcnt lgkmcnt(4)
	v_mfma_f32_32x32x16_bf16 v[82:97], v[66:69], v[136:139], 0
	s_waitcnt lgkmcnt(3)
	v_mfma_f32_32x32x16_bf16 v[82:97], v[208:211], v[144:147], v[82:97]
	ds_read_b128 v[208:211], v183 offset:57344
	s_waitcnt lgkmcnt(3)
	v_mfma_f32_32x32x16_bf16 v[66:81], v[238:241], v[136:139], 0
	ds_read_b128 v[238:241], v184 offset:49152
	s_waitcnt lgkmcnt(3)
	v_mfma_f32_32x32x16_bf16 v[66:81], v[242:245], v[144:147], v[66:81]
	ds_read_b128 v[242:245], v184 offset:57344
	s_waitcnt lgkmcnt(3)
	v_mfma_f32_32x32x16_bf16 v[82:97], v[246:249], v[132:135], v[82:97]
	ds_read_b128 v[246:249], v185 offset:49152
	s_waitcnt lgkmcnt(3)
	v_mfma_f32_32x32x16_bf16 v[66:81], v[208:211], v[132:135], v[66:81]
	ds_read_b128 v[208:211], v185 offset:57344
	s_waitcnt lgkmcnt(3)
	v_mfma_f32_32x32x16_bf16 v[82:97], v[238:241], v[140:143], v[82:97]
	ds_read_b128 v[238:241], v186 offset:49152
	s_waitcnt lgkmcnt(3)
	v_mfma_f32_32x32x16_bf16 v[66:81], v[242:245], v[140:143], v[66:81]
	ds_read_b128 v[242:245], v186 offset:57344
	s_waitcnt lgkmcnt(3)
	v_mfma_f32_32x32x16_bf16 v[82:97], v[246:249], v[152:155], v[82:97]
	ds_read_b128 v[246:249], v189 offset:49152
	s_waitcnt lgkmcnt(3)
	v_mfma_f32_32x32x16_bf16 v[66:81], v[208:211], v[152:155], v[66:81]
	ds_read_b128 v[208:211], v189 offset:57344
	s_waitcnt lgkmcnt(3)
	v_mfma_f32_32x32x16_bf16 v[82:97], v[238:241], v[160:163], v[82:97]
	ds_read_b128 v[238:241], v190 offset:49152
	s_waitcnt lgkmcnt(3)
	v_mfma_f32_32x32x16_bf16 v[66:81], v[242:245], v[160:163], v[66:81]
	ds_read_b128 v[242:245], v190 offset:57344
	s_waitcnt lgkmcnt(3)
	v_mfma_f32_32x32x16_bf16 v[82:97], v[246:249], v[148:151], v[82:97]
	s_waitcnt lgkmcnt(2)
	v_mfma_f32_32x32x16_bf16 v[66:81], v[208:211], v[148:151], v[66:81]
	s_waitcnt lgkmcnt(1)
	v_mfma_f32_32x32x16_bf16 v[82:97], v[238:241], v[156:159], v[82:97]
	s_waitcnt lgkmcnt(0)
	v_mfma_f32_32x32x16_bf16 v[66:81], v[242:245], v[156:159], v[66:81]
	s_cbranch_vccnz .LBB0_563
	v_add_u32_e32 v172, 0xffffff3f, v197
	v_cmp_gt_u32_e32 vcc, s33, v172
	s_cbranch_vccz .LBB0_563
	v_add_u32_e32 v172, v167, v196
	v_add_u32_e32 v173, 0xffffff3f, v172
	v_cmp_lt_u32_e32 vcc, s67, v173
	v_add_u32_e32 v173, 0xffffff1f, v172
	s_nop 0
	v_cndmask_b32_e32 v82, v206, v82, vcc
	v_cmp_lt_u32_e32 vcc, s67, v173
	v_add_u32_e32 v173, 0xffffff3e, v172
	s_nop 0
	v_cndmask_b32_e32 v66, v206, v66, vcc
	v_cmp_lt_u32_e32 vcc, s67, v173
	v_add_u32_e32 v173, 0xffffff1e, v172
	s_nop 0
	v_cndmask_b32_e32 v83, v206, v83, vcc
	v_cmp_lt_u32_e32 vcc, s67, v173
	v_add_u32_e32 v173, 0xffffff3d, v172
	s_nop 0
	v_cndmask_b32_e32 v67, v206, v67, vcc
	v_cmp_lt_u32_e32 vcc, s67, v173
	v_add_u32_e32 v173, 0xffffff1d, v172
	s_nop 0
	v_cndmask_b32_e32 v84, v206, v84, vcc
	v_cmp_lt_u32_e32 vcc, s67, v173
	v_add_u32_e32 v173, 0xffffff3c, v172
	s_nop 0
	v_cndmask_b32_e32 v68, v206, v68, vcc
	v_cmp_lt_u32_e32 vcc, s67, v173
	v_add_u32_e32 v173, 0xffffff1c, v172
	s_nop 0
	v_cndmask_b32_e32 v85, v206, v85, vcc
	v_cmp_lt_u32_e32 vcc, s67, v173
	v_add_u32_e32 v173, 0xffffff37, v172
	s_nop 0
	v_cndmask_b32_e32 v69, v206, v69, vcc
	v_cmp_lt_u32_e32 vcc, s67, v173
	v_add_u32_e32 v173, 0xffffff17, v172
	s_nop 0
	v_cndmask_b32_e32 v86, v206, v86, vcc
	v_cmp_lt_u32_e32 vcc, s67, v173
	v_add_u32_e32 v173, 0xffffff36, v172
	s_nop 0
	v_cndmask_b32_e32 v70, v206, v70, vcc
	v_cmp_lt_u32_e32 vcc, s67, v173
	v_add_u32_e32 v173, 0xffffff16, v172
	s_nop 0
	v_cndmask_b32_e32 v87, v206, v87, vcc
	v_cmp_lt_u32_e32 vcc, s67, v173
	v_add_u32_e32 v173, 0xffffff35, v172
	s_nop 0
	v_cndmask_b32_e32 v71, v206, v71, vcc
	v_cmp_lt_u32_e32 vcc, s67, v173
	v_add_u32_e32 v173, 0xffffff15, v172
	s_nop 0
	v_cndmask_b32_e32 v88, v206, v88, vcc
	v_cmp_lt_u32_e32 vcc, s67, v173
	v_add_u32_e32 v173, 0xffffff34, v172
	s_nop 0
	v_cndmask_b32_e32 v72, v206, v72, vcc
	v_cmp_lt_u32_e32 vcc, s67, v173
	v_add_u32_e32 v173, 0xffffff14, v172
	s_nop 0
	v_cndmask_b32_e32 v89, v206, v89, vcc
	v_cmp_lt_u32_e32 vcc, s67, v173
	v_add_u32_e32 v173, 0xffffff2f, v172
	s_nop 0
	v_cndmask_b32_e32 v73, v206, v73, vcc
	v_cmp_lt_u32_e32 vcc, s67, v173
	v_add_u32_e32 v173, 0xffffff0f, v172
	s_nop 0
	v_cndmask_b32_e32 v90, v206, v90, vcc
	v_cmp_lt_u32_e32 vcc, s67, v173
	v_add_u32_e32 v173, 0xffffff2e, v172
	s_nop 0
	v_cndmask_b32_e32 v74, v206, v74, vcc
	v_cmp_lt_u32_e32 vcc, s67, v173
	v_add_u32_e32 v173, 0xffffff0e, v172
	s_nop 0
	v_cndmask_b32_e32 v91, v206, v91, vcc
	v_cmp_lt_u32_e32 vcc, s67, v173
	v_add_u32_e32 v173, 0xffffff2d, v172
	s_nop 0
	v_cndmask_b32_e32 v75, v206, v75, vcc
	v_cmp_lt_u32_e32 vcc, s67, v173
	v_add_u32_e32 v173, 0xffffff0d, v172
	s_nop 0
	v_cndmask_b32_e32 v92, v206, v92, vcc
	v_cmp_lt_u32_e32 vcc, s67, v173
	v_add_u32_e32 v173, 0xffffff2c, v172
	s_nop 0
	v_cndmask_b32_e32 v76, v206, v76, vcc
	v_cmp_lt_u32_e32 vcc, s67, v173
	v_add_u32_e32 v173, 0xffffff0c, v172
	s_nop 0
	v_cndmask_b32_e32 v93, v206, v93, vcc
	v_cmp_lt_u32_e32 vcc, s67, v173
	v_add_u32_e32 v173, 0xffffff27, v172
	s_nop 0
	v_cndmask_b32_e32 v77, v206, v77, vcc
	v_cmp_lt_u32_e32 vcc, s67, v173
	v_add_u32_e32 v173, 0xffffff07, v172
	s_nop 0
	v_cndmask_b32_e32 v94, v206, v94, vcc
	v_cmp_lt_u32_e32 vcc, s67, v173
	v_add_u32_e32 v173, 0xffffff26, v172
	s_nop 0
	v_cndmask_b32_e32 v78, v206, v78, vcc
	v_cmp_lt_u32_e32 vcc, s67, v173
	v_add_u32_e32 v173, 0xffffff06, v172
	s_nop 0
	v_cndmask_b32_e32 v95, v206, v95, vcc
	v_cmp_lt_u32_e32 vcc, s67, v173
	v_add_u32_e32 v173, 0xffffff25, v172
	s_nop 0
	v_cndmask_b32_e32 v79, v206, v79, vcc
	v_cmp_lt_u32_e32 vcc, s67, v173
	v_add_u32_e32 v173, 0xffffff05, v172
	s_nop 0
	v_cndmask_b32_e32 v96, v206, v96, vcc
	v_cmp_lt_u32_e32 vcc, s67, v173
	v_add_u32_e32 v173, 0xffffff24, v172
	v_add_u32_e32 v172, 0xffffff04, v172
	v_cndmask_b32_e32 v80, v206, v80, vcc
	v_cmp_lt_u32_e32 vcc, s67, v173
	s_nop 1
	v_cndmask_b32_e32 v97, v206, v97, vcc
	v_cmp_lt_u32_e32 vcc, s67, v172
	s_nop 1
	v_cndmask_b32_e32 v81, v206, v81, vcc

.LBB0_571:
	s_waitcnt lgkmcnt(0)
	s_barrier
	ds_read_b128 v[98:101], v180 offset:32768
	ds_read_b128 v[210:213], v182 offset:32768
	ds_read_b128 v[238:241], v180 offset:40960
	ds_read_b128 v[242:245], v182 offset:40960
	ds_read_b128 v[246:249], v183 offset:32768
	s_or_b64 s[40:41], s[30:31], s[40:41]
	s_and_b64 vcc, exec, s[40:41]
	s_waitcnt lgkmcnt(4)
	v_mfma_f32_32x32x16_bf16 v[114:129], v[98:101], v[136:139], 0
	s_waitcnt lgkmcnt(3)
	v_mfma_f32_32x32x16_bf16 v[114:129], v[210:213], v[144:147], v[114:129]
	ds_read_b128 v[210:213], v183 offset:40960
	s_waitcnt lgkmcnt(3)
	v_mfma_f32_32x32x16_bf16 v[98:113], v[238:241], v[136:139], 0
	ds_read_b128 v[238:241], v184 offset:32768
	s_waitcnt lgkmcnt(3)
	v_mfma_f32_32x32x16_bf16 v[98:113], v[242:245], v[144:147], v[98:113]
	ds_read_b128 v[242:245], v184 offset:40960
	s_waitcnt lgkmcnt(3)
	v_mfma_f32_32x32x16_bf16 v[114:129], v[246:249], v[132:135], v[114:129]
	ds_read_b128 v[246:249], v185 offset:32768
	s_waitcnt lgkmcnt(3)
	v_mfma_f32_32x32x16_bf16 v[98:113], v[210:213], v[132:135], v[98:113]
	ds_read_b128 v[210:213], v185 offset:40960
	s_waitcnt lgkmcnt(3)
	v_mfma_f32_32x32x16_bf16 v[114:129], v[238:241], v[140:143], v[114:129]
	ds_read_b128 v[238:241], v186 offset:32768
	s_waitcnt lgkmcnt(3)
	v_mfma_f32_32x32x16_bf16 v[98:113], v[242:245], v[140:143], v[98:113]
	ds_read_b128 v[242:245], v186 offset:40960
	s_waitcnt lgkmcnt(3)
	v_mfma_f32_32x32x16_bf16 v[114:129], v[246:249], v[152:155], v[114:129]
	ds_read_b128 v[246:249], v189 offset:32768
	s_waitcnt lgkmcnt(3)
	v_mfma_f32_32x32x16_bf16 v[98:113], v[210:213], v[152:155], v[98:113]
	ds_read_b128 v[210:213], v189 offset:40960
	s_waitcnt lgkmcnt(3)
	v_mfma_f32_32x32x16_bf16 v[114:129], v[238:241], v[160:163], v[114:129]
	ds_read_b128 v[238:241], v190 offset:32768
	s_waitcnt lgkmcnt(3)
	v_mfma_f32_32x32x16_bf16 v[98:113], v[242:245], v[160:163], v[98:113]
	ds_read_b128 v[242:245], v190 offset:40960
	s_waitcnt lgkmcnt(3)
	v_mfma_f32_32x32x16_bf16 v[114:129], v[246:249], v[148:151], v[114:129]
	s_waitcnt lgkmcnt(2)
	v_mfma_f32_32x32x16_bf16 v[98:113], v[210:213], v[148:151], v[98:113]
	s_waitcnt lgkmcnt(1)
	v_mfma_f32_32x32x16_bf16 v[114:129], v[238:241], v[156:159], v[114:129]
	s_waitcnt lgkmcnt(0)
	v_mfma_f32_32x32x16_bf16 v[98:113], v[242:245], v[156:159], v[98:113]
	s_cbranch_vccnz .LBB0_574
	v_add_u32_e32 v172, 0xfffffeff, v197
	v_cmp_gt_u32_e32 vcc, s33, v172
	s_cbranch_vccz .LBB0_574
	v_add_u32_e32 v172, v167, v196
	v_add_co_u32_e32 v173, vcc, 0xfffffeff, v172
	v_add_u32_e32 v173, 0xfffffedf, v172
	s_nop 1
	v_cndmask_b32_e32 v114, v114, v206, vcc
	v_cmp_lt_u32_e32 vcc, s67, v173
	v_add_u32_e32 v173, 0xfffffefe, v172
	s_nop 0
	v_cndmask_b32_e32 v98, v206, v98, vcc
	v_cmp_lt_u32_e32 vcc, s67, v173
	v_add_u32_e32 v173, 0xfffffede, v172
	s_nop 0
	v_cndmask_b32_e32 v115, v206, v115, vcc
	v_cmp_lt_u32_e32 vcc, s67, v173
	v_add_u32_e32 v173, 0xfffffefd, v172
	s_nop 0
	v_cndmask_b32_e32 v99, v206, v99, vcc
	v_cmp_lt_u32_e32 vcc, s67, v173
	v_add_u32_e32 v173, 0xfffffedd, v172
	s_nop 0
	v_cndmask_b32_e32 v116, v206, v116, vcc
	v_cmp_lt_u32_e32 vcc, s67, v173
	v_add_u32_e32 v173, 0xfffffefc, v172
	s_nop 0
	v_cndmask_b32_e32 v100, v206, v100, vcc
	v_cmp_lt_u32_e32 vcc, s67, v173
	v_add_u32_e32 v173, 0xfffffedc, v172
	s_nop 0
	v_cndmask_b32_e32 v117, v206, v117, vcc
	v_cmp_lt_u32_e32 vcc, s67, v173
	v_add_u32_e32 v173, 0xfffffef7, v172
	s_nop 0
	v_cndmask_b32_e32 v101, v206, v101, vcc
	v_cmp_lt_u32_e32 vcc, s67, v173
	v_add_u32_e32 v173, 0xfffffed7, v172
	s_nop 0
	v_cndmask_b32_e32 v118, v206, v118, vcc
	v_cmp_lt_u32_e32 vcc, s67, v173
	v_add_u32_e32 v173, 0xfffffef6, v172
	s_nop 0
	v_cndmask_b32_e32 v102, v206, v102, vcc
	v_cmp_lt_u32_e32 vcc, s67, v173
	v_add_u32_e32 v173, 0xfffffed6, v172
	s_nop 0
	v_cndmask_b32_e32 v119, v206, v119, vcc
	v_cmp_lt_u32_e32 vcc, s67, v173
	v_add_u32_e32 v173, 0xfffffef5, v172
	s_nop 0
	v_cndmask_b32_e32 v103, v206, v103, vcc
	v_cmp_lt_u32_e32 vcc, s67, v173
	v_add_u32_e32 v173, 0xfffffed5, v172
	s_nop 0
	v_cndmask_b32_e32 v120, v206, v120, vcc
	v_cmp_lt_u32_e32 vcc, s67, v173
	v_add_u32_e32 v173, 0xfffffef4, v172
	s_nop 0
	v_cndmask_b32_e32 v104, v206, v104, vcc
	v_cmp_lt_u32_e32 vcc, s67, v173
	v_add_u32_e32 v173, 0xfffffed4, v172
	s_nop 0
	v_cndmask_b32_e32 v121, v206, v121, vcc
	v_cmp_lt_u32_e32 vcc, s67, v173
	v_add_u32_e32 v173, 0xfffffeef, v172
	s_nop 0
	v_cndmask_b32_e32 v105, v206, v105, vcc
	v_cmp_lt_u32_e32 vcc, s67, v173
	v_add_u32_e32 v173, 0xfffffecf, v172
	s_nop 0
	v_cndmask_b32_e32 v122, v206, v122, vcc
	v_cmp_lt_u32_e32 vcc, s67, v173
	v_add_u32_e32 v173, 0xfffffeee, v172
	s_nop 0
	v_cndmask_b32_e32 v106, v206, v106, vcc
	v_cmp_lt_u32_e32 vcc, s67, v173
	v_add_u32_e32 v173, 0xfffffece, v172
	s_nop 0
	v_cndmask_b32_e32 v123, v206, v123, vcc
	v_cmp_lt_u32_e32 vcc, s67, v173
	v_add_u32_e32 v173, 0xfffffeed, v172
	s_nop 0
	v_cndmask_b32_e32 v107, v206, v107, vcc
	v_cmp_lt_u32_e32 vcc, s67, v173
	v_add_u32_e32 v173, 0xfffffecd, v172
	s_nop 0
	v_cndmask_b32_e32 v124, v206, v124, vcc
	v_cmp_lt_u32_e32 vcc, s67, v173
	v_add_u32_e32 v173, 0xfffffeec, v172
	s_nop 0
	v_cndmask_b32_e32 v108, v206, v108, vcc
	v_cmp_lt_u32_e32 vcc, s67, v173
	v_add_u32_e32 v173, 0xfffffecc, v172
	s_nop 0
	v_cndmask_b32_e32 v125, v206, v125, vcc
	v_cmp_lt_u32_e32 vcc, s67, v173
	v_add_u32_e32 v173, 0xfffffee7, v172
	s_nop 0
	v_cndmask_b32_e32 v109, v206, v109, vcc
	v_cmp_lt_u32_e32 vcc, s67, v173
	v_add_u32_e32 v173, 0xfffffec7, v172
	s_nop 0
	v_cndmask_b32_e32 v126, v206, v126, vcc
	v_cmp_lt_u32_e32 vcc, s67, v173
	v_add_u32_e32 v173, 0xfffffee6, v172
	s_nop 0
	v_cndmask_b32_e32 v110, v206, v110, vcc
	v_cmp_lt_u32_e32 vcc, s67, v173
	v_add_u32_e32 v173, 0xfffffec6, v172
	s_nop 0
	v_cndmask_b32_e32 v127, v206, v127, vcc
	v_cmp_lt_u32_e32 vcc, s67, v173
	v_add_u32_e32 v173, 0xfffffee5, v172
	s_nop 0
	v_cndmask_b32_e32 v111, v206, v111, vcc
	v_cmp_lt_u32_e32 vcc, s67, v173
	v_add_u32_e32 v173, 0xfffffec5, v172
	s_nop 0
	v_cndmask_b32_e32 v128, v206, v128, vcc
	v_cmp_lt_u32_e32 vcc, s67, v173
	v_add_u32_e32 v173, 0xfffffee4, v172
	v_add_u32_e32 v172, 0xfffffec4, v172
	v_cndmask_b32_e32 v112, v206, v112, vcc
	v_cmp_lt_u32_e32 vcc, s67, v173
	s_nop 1
	v_cndmask_b32_e32 v129, v206, v129, vcc
	v_cmp_lt_u32_e32 vcc, s67, v172
	s_nop 1
	v_cndmask_b32_e32 v113, v206, v113, vcc
